# chunk-scan chain: group-A half 0 released to its loader right after the ti=0 section, half-1 landed-poll deferred to the ti=1 section start
# speedup vs baseline: 1.0101x; 1.0101x over previous
; #define LAS __attribute__((address_space(3)))
; #define REP(k) for (int rep_ = 0; rep_ < 1 + ((PROBE_MASK >> (k)) & 1); ++rep_)
; __device__ __forceinline__ void scan_loader(const P& p, int id, int role, LAS unsigned char* ldsw, int lane) {
;     volatile LAS unsigned* FL = (volatile LAS unsigned*)(ldsw + SCAN_FLAGS_OFF);
;     const int r = lane & 31, hh = lane >> 5;
;     const bool gla = id < 64; const int q = gla ? id : id - 64;
;     const int s = q >> 5, h = gla ? (q >> 3) & 3 : (q >> 2) & 7, sl = gla ? q & 7 : q & 3;
;     LAS unsigned char* bufA = ldsw + 16384; LAS unsigned char* bufB = ldsw + 16384 + (gla ? 28 : 40) * 1024;
; #pragma unroll 1
;     for (int n = 0; n < NCH; ++n) {
;         const int ch = gla ? (s * 64 + n) * 4 + h : (s * 64 + n) * 8 + h;
;         if (!lds_wait_ge<true>(FL + (role < 2 ? 3 : 4), (unsigned)n, FL + 5)) break;
; __global__ void __launch_bounds__(512, 2) mega(Args a) {
;     ...
;             const int nsb = G < 128 ? G : 128;
;             const int nrole = SCAN_LOADERS ? 4 : 1;
;             const bool scan_block = bx < nsb;
;             if (scan_block && wave < nrole) {
;                 REP(13) for (int id = bx; id < 128; id += G) {
;                     if (tid_p < 16) {}
;                     if (wave == 0) {
;                         if (id < 64) gla_scan_task(p, l, id >> 5, (id >> 3) & 3, id & 7, lds, lane);
;                         else delta_scan_task(p, l, (id - 64) >> 5, ((id - 64) >> 2) & 7, (id - 64) & 3, lds, lane);
;                     } else scan_loader(p, id, wave - 1, lds, lane);
.LBB0_1422:
	s_and_b64 vcc, exec, s[0:1]
	s_cbranch_vccz .LBB0_1558
	v_readlane_b32 s0, v254, 63
	s_lshl_b32 s0, s0, 3
	s_cmp_gt_u32 s92, 63
	v_readlane_b32 s1, v248, 0
	v_writelane_b32 v248, s0, 4
	s_cselect_b64 s[24:25], -1, 0
	s_add_i32 s0, s55, -1
	s_cmp_gt_i32 s55, 2
	s_cselect_b64 s[38:39], -1, 0
	s_cmp_lt_i32 s55, 3
	s_cselect_b32 s1, 12, 16
	s_add_i32 s17, s1, 0
	s_cmp_eq_u32 s55, 1
	s_cselect_b32 s17, 24, s17
	s_lshl_b32 s1, s0, 12
	s_lshl_b32 s4, s0, 5
	s_add_i32 s19, s1, 0
	s_ashr_i32 s5, s4, 31
	s_lshl_b32 s18, s0, 13
	s_add_i32 s20, s19, 0xcc00
	s_cmp_eq_u32 s0, 0
	v_and_b32_e32 v138, 31, v178
	s_cselect_b64 s[0:1], -1, 0
	s_lshl_b32 s6, s55, 2
	v_readlane_b32 s60, v250, 62
	v_or_b32_e32 v144, s4, v138
	v_mov_b32_e32 v145, s5
	s_add_i32 s21, s19, 0x9c00
	s_add_i32 s22, s6, 0
	s_lshl_b64 s[4:5], s[4:5], 2
	v_readlane_b32 s70, v251, 8
	v_lshrrev_b32_e32 v2, 5, v161
	v_readlane_b32 s71, v251, 9
	s_add_u32 s4, s70, s4
	s_movk_i32 s6, 0x110
	v_lshlrev_b32_e32 v3, 4, v161
	v_readlane_b32 s8, v249, 0
	v_lshlrev_b32_e32 v142, 7, v138
	v_mov_b32_e32 v143, v163
	v_writelane_b32 v248, s0, 2
	v_readlane_b32 s61, v250, 63
	v_readlane_b32 s62, v251, 0
	v_readlane_b32 s63, v251, 1
	v_readlane_b32 s64, v251, 2
	v_readlane_b32 s65, v251, 3
	v_readlane_b32 s66, v251, 4
	v_readlane_b32 s67, v251, 5
	v_readlane_b32 s68, v251, 6
	v_readlane_b32 s69, v251, 7
	v_readlane_b32 s72, v251, 10
	v_readlane_b32 s73, v251, 11
	v_readlane_b32 s74, v251, 12
	v_readlane_b32 s75, v251, 13
	s_addc_u32 s5, s71, s5
	v_mad_u32_u24 v194, v138, s6, 0
	v_lshlrev_b32_e32 v148, 4, v2
	v_add_u32_e32 v209, 0, v3
	v_readlane_b32 s9, v249, 1
	v_readlane_b32 s10, v249, 2
	v_readlane_b32 s11, v249, 3
	v_mov_b32_e32 v149, v163
	v_lshlrev_b32_e32 v140, 3, v2
	v_lshlrev_b32_e32 v1, 2, v2
	v_writelane_b32 v248, s1, 3
	v_cmp_eq_u32_e64 s[0:1], 0, v161
	v_lshlrev_b64 v[146:147], 7, v[144:145]
	v_lshlrev_b32_e32 v139, 8, v138
	v_lshlrev_b32_e32 v141, 3, v161
	v_sub_u32_e32 v195, v194, v142
	v_add_u32_e32 v210, 0xe000, v209
	v_lshlrev_b32_e32 v211, 14, v2
	v_lshlrev_b32_e32 v150, 11, v2
	v_mov_b32_e32 v151, v163
	v_lshlrev_b32_e32 v152, 12, v2
	v_mov_b32_e32 v153, v163
	v_lshl_add_u64 v[154:155], s[8:9], 0, v[142:143]
	v_lshl_add_u64 v[156:157], s[10:11], 0, v[142:143]
	v_lshl_add_u64 v[158:159], s[62:63], 0, v[142:143]
	v_lshl_add_u64 v[160:161], s[68:69], 0, v[148:149]
	v_lshl_add_u64 v[178:179], s[72:73], 0, v[148:149]
	v_lshl_add_u64 v[180:181], s[74:75], 0, v[148:149]
	v_lshl_add_u64 v[182:183], s[4:5], 0, v[148:149]
	v_lshl_add_u64 v[184:185], s[64:65], 0, v[148:149]
	v_lshl_add_u64 v[186:187], s[60:61], 0, v[148:149]
	v_lshl_add_u64 v[188:189], s[66:67], 0, v[148:149]
	s_add_i32 s23, s19, 0xc400
	s_add_i32 s36, s19, 0xc800
	s_mov_b32 s37, s30
	s_cmp_gt_u32 s30, 127
	s_cbranch_scc1 .Lscanperm_done
	s_and_b32 s100, s30, 7
	s_lshl_b32 s100, s100, 3
	s_bfe_u32 s37, s30, 0x30003
	s_or_b32 s37, s37, s100
	s_cmp_lt_u32 s30, 64
	s_cbranch_scc1 .Lscanperm_done
	s_sub_u32 s100, s30, 64
	s_and_b32 s37, s100, 15
	s_lshl_b32 s37, s37, 2
	s_lshr_b32 s100, s100, 4
	s_or_b32 s37, s37, s100
	s_add_u32 s37, s37, 64

; #define LAS __attribute__((address_space(3)))
; __device__ __forceinline__ f32x16 mma32(bf16x8 a, bf16x8 b, f32x16 c) { return __builtin_amdgcn_mfma_f32_32x32x16_bf16(a, b, c, 0, 0, 0); }
; #define LDS_WAIT() asm volatile("s_waitcnt lgkmcnt(0)" ::: "memory")
; #define VM_WAIT_N(n) asm volatile("s_waitcnt vmcnt(" #n ")" ::: "memory")
; __device__ __forceinline__ void delta_scan_task(const P& p, int l, int s, int h, int sl, LAS unsigned char* ldsw, int lane) {
;     ...
;         if (SCAN_LOADERS) { LDS_WAIT(); lds_wait_ge(FL + 0, (unsigned)n + 1u, FL + 5); lds_wait_ge(FL + 1, (unsigned)n + 1u, FL + 5); }
;         else { VM_WAIT_N(24); LDS_WAIT(); }
;         f32x16 u[2], o[2];
; #pragma unroll
;         for (int ti = 0; ti < 2; ++ti) {
; #pragma unroll
;             for (int g = 0; g < 4; ++g) { const f32x4v ub4 = FRAGF4(bufA, 32 + ti * 4 + g, lane); u[ti][4 * g] = ub4.x; u[ti][4 * g + 1] = ub4.y; u[ti][4 * g + 2] = ub4.z; u[ti][4 * g + 3] = ub4.w; }
;             o[ti] = zero16();
; #pragma unroll
;             for (int ks = 0; ks < 8; ++ks) {
;                 const bf16x8 b = *(const LAS bf16x8*)(ST + r * 136 + 16 * ks + 8 * hh);
;                 u[ti] = mma32(FRAG16(bufA, ti * 8 + ks, lane), b, u[ti]); o[ti] = mma32(FRAG16(bufA, 16 + ti * 8 + ks, lane), b, o[ti]);
;             }
;         }
.LBB0_1491:
.LBB0_1502:
	s_waitcnt lgkmcnt(0)
	v_add_u32_e32 v172, v194, v148
	s_add_i32 s34, s7, 1
	ds_read_b128 v[98:101], v209 offset:49152
	ds_read_b128 v[102:105], v209 offset:50176
	ds_read_b128 v[106:109], v209 offset:51200
	ds_read_b128 v[110:113], v209 offset:52224
	ds_read_b128 v[70:73], v172
	ds_read_b128 v[236:239], v209 offset:16384
	ds_read_b128 v[240:243], v209 offset:32768
	ds_read_b128 v[130:133], v172 offset:32
	ds_read_b128 v[244:247], v209 offset:17408
	ds_read_b128 v[168:171], v209 offset:33792
	ds_read_b128 v[212:215], v172 offset:64
	ds_read_b128 v[232:235], v209 offset:18432
	s_waitcnt lgkmcnt(6)
	v_mfma_f32_32x32x16_bf16 v[98:113], v[236:239], v[70:73], v[98:113]
	ds_read_b128 v[66:69], v209 offset:34816
	s_waitcnt lgkmcnt(6)
	v_mfma_f32_32x32x16_bf16 v[82:97], v[240:243], v[70:73], 0
	ds_read_b128 v[134:137], v172 offset:96
	ds_read_b128 v[236:239], v209 offset:19456
	s_waitcnt lgkmcnt(6)
	v_mfma_f32_32x32x16_bf16 v[98:113], v[244:247], v[130:133], v[98:113]
	ds_read_b128 v[240:243], v209 offset:35840
	s_waitcnt lgkmcnt(6)
	v_mfma_f32_32x32x16_bf16 v[82:97], v[168:171], v[130:133], v[82:97]
	ds_read_b128 v[216:219], v172 offset:128
	ds_read_b128 v[244:247], v209 offset:20480
	s_waitcnt lgkmcnt(6)
	v_mfma_f32_32x32x16_bf16 v[98:113], v[232:235], v[212:215], v[98:113]
	ds_read_b128 v[168:171], v209 offset:36864
	s_waitcnt lgkmcnt(6)
	v_mfma_f32_32x32x16_bf16 v[82:97], v[66:69], v[212:215], v[82:97]
	ds_read_b128 v[220:223], v172 offset:160
	ds_read_b128 v[232:235], v209 offset:21504
	s_waitcnt lgkmcnt(6)
	v_mfma_f32_32x32x16_bf16 v[98:113], v[236:239], v[134:137], v[98:113]
	ds_read_b128 v[66:69], v209 offset:37888
	s_waitcnt lgkmcnt(6)
	v_mfma_f32_32x32x16_bf16 v[82:97], v[240:243], v[134:137], v[82:97]
	ds_read_b128 v[224:227], v172 offset:192
	ds_read_b128 v[236:239], v209 offset:22528
	s_waitcnt lgkmcnt(6)
	v_mfma_f32_32x32x16_bf16 v[98:113], v[244:247], v[216:219], v[98:113]
	ds_read_b128 v[240:243], v209 offset:38912
	s_waitcnt lgkmcnt(6)
	v_mfma_f32_32x32x16_bf16 v[82:97], v[168:171], v[216:219], v[82:97]
	ds_read_b128 v[228:231], v172 offset:224
	ds_read_b128 v[244:247], v209 offset:23552
	s_waitcnt lgkmcnt(6)
	v_mfma_f32_32x32x16_bf16 v[98:113], v[232:235], v[220:223], v[98:113]
	ds_read_b128 v[168:171], v209 offset:39936
	s_waitcnt lgkmcnt(6)
	v_mfma_f32_32x32x16_bf16 v[82:97], v[66:69], v[220:223], v[82:97]
	s_waitcnt lgkmcnt(4)
	v_mfma_f32_32x32x16_bf16 v[98:113], v[236:239], v[224:227], v[98:113]
	s_waitcnt lgkmcnt(3)
	v_mfma_f32_32x32x16_bf16 v[82:97], v[240:243], v[224:227], v[82:97]
	s_waitcnt lgkmcnt(1)
	v_mfma_f32_32x32x16_bf16 v[98:113], v[244:247], v[228:231], v[98:113]
	s_waitcnt lgkmcnt(0)
	v_mfma_f32_32x32x16_bf16 v[82:97], v[168:171], v[228:231], v[82:97]
	s_and_saveexec_b64 s[100:101], s[0:1]
	v_mov_b32_e32 v255, s34
	ds_write_b32 v163, v255 offset:13336
	s_or_b64 exec, exec, s[100:101]
	s_waitcnt lgkmcnt(0)
	ds_read_b32 v66, v163 offset:13316
	s_waitcnt lgkmcnt(0)
	v_cmp_lt_u32_e32 vcc, s7, v66
	s_cbranch_vccnz .Ldp1_done
	s_mov_b32 s4, 1
	s_branch .Ldp1_1494

; __device__ __forceinline__ unsigned pk2(float lo, float hi) { f32x2_t v = {lo, hi}; bf16x2_t b = __builtin_convertvector(v, bf16x2_t); return __builtin_bit_cast(unsigned, b); }
; #define LAS __attribute__((address_space(3)))
; __device__ __forceinline__ f32x16 mma32(bf16x8 a, bf16x8 b, f32x16 c) { return __builtin_amdgcn_mfma_f32_32x32x16_bf16(a, b, c, 0, 0, 0); }
; #define LDS_WAIT() asm volatile("s_waitcnt lgkmcnt(0)" ::: "memory")
; __device__ __forceinline__ void delta_scan_task(const P& p, int l, int s, int h, int sl, LAS unsigned char* ldsw, int lane) {
;     ...
;         for (int ti = 0; ti < 2; ++ti) {
; #pragma unroll
;             for (int g = 0; g < 4; ++g) { const f32x4v ub4 = FRAGF4(bufA, 32 + ti * 4 + g, lane); u[ti][4 * g] = ub4.x; u[ti][4 * g + 1] = ub4.y; u[ti][4 * g + 2] = ub4.z; u[ti][4 * g + 3] = ub4.w; }
;             o[ti] = zero16();
; #pragma unroll
;             for (int ks = 0; ks < 8; ++ks) {
;                 const bf16x8 b = *(const LAS bf16x8*)(ST + r * 136 + 16 * ks + 8 * hh);
;                 u[ti] = mma32(FRAG16(bufA, ti * 8 + ks, lane), b, u[ti]); o[ti] = mma32(FRAG16(bufA, 16 + ti * 8 + ks, lane), b, o[ti]);
;             }
;         }
; #pragma unroll
;         for (int ti = 0; ti < 2; ++ti)
; #pragma unroll
;             for (int g = 0; g < 4; ++g) { u32x2v w; w.x = pk2(u[ti][4 * g], u[ti][4 * g + 1]); w.y = pk2(u[ti][4 * g + 2], u[ti][4 * g + 3]); *(LAS u32x2v*)(UT + r * 72 + 32 * ti + 8 * g + 4 * hh) = w; }
;         LDS_WAIT();
;         if (SCAN_LOADERS) { if (lane == 0) FL[3] = (unsigned)n + 1u; lds_wait_ge(FL + 2, (unsigned)n + 1u, FL + 5); }
.Ldp1_done:
	s_waitcnt lgkmcnt(0)
	ds_read_b128 v[114:117], v209 offset:53248
	ds_read_b128 v[118:121], v209 offset:54272
	ds_read_b128 v[122:125], v209 offset:55296
	ds_read_b128 v[126:129], v209 offset:56320
	ds_read_b128 v[236:239], v209 offset:24576
	ds_read_b128 v[240:243], v209 offset:40960
	ds_read_b128 v[244:247], v209 offset:25600
	ds_read_b128 v[168:171], v209 offset:41984
	ds_read_b128 v[232:235], v209 offset:26624
	s_waitcnt lgkmcnt(4)
	v_mfma_f32_32x32x16_bf16 v[114:129], v[236:239], v[70:73], v[114:129]
	ds_read_b128 v[236:239], v209 offset:43008
	s_waitcnt lgkmcnt(4)
	v_mfma_f32_32x32x16_bf16 v[66:81], v[240:243], v[70:73], 0
	ds_read_b128 v[240:243], v209 offset:27648
	s_waitcnt lgkmcnt(4)
	v_mfma_f32_32x32x16_bf16 v[114:129], v[244:247], v[130:133], v[114:129]
	ds_read_b128 v[244:247], v209 offset:44032
	s_waitcnt lgkmcnt(4)
	v_mfma_f32_32x32x16_bf16 v[66:81], v[168:171], v[130:133], v[66:81]
	ds_read_b128 v[168:171], v209 offset:28672
	s_waitcnt lgkmcnt(4)
	v_mfma_f32_32x32x16_bf16 v[114:129], v[232:235], v[212:215], v[114:129]
	ds_read_b128 v[232:235], v209 offset:45056
	s_waitcnt lgkmcnt(4)
	v_mfma_f32_32x32x16_bf16 v[66:81], v[236:239], v[212:215], v[66:81]
	ds_read_b128 v[236:239], v209 offset:29696
	s_waitcnt lgkmcnt(4)
	v_mfma_f32_32x32x16_bf16 v[114:129], v[240:243], v[134:137], v[114:129]
	ds_read_b128 v[240:243], v209 offset:46080
	s_waitcnt lgkmcnt(4)
	v_mfma_f32_32x32x16_bf16 v[66:81], v[244:247], v[134:137], v[66:81]
	ds_read_b128 v[244:247], v209 offset:30720
	s_waitcnt lgkmcnt(4)
	v_mfma_f32_32x32x16_bf16 v[114:129], v[168:171], v[216:219], v[114:129]
	ds_read_b128 v[168:171], v209 offset:47104
	s_waitcnt lgkmcnt(4)
	v_mfma_f32_32x32x16_bf16 v[66:81], v[232:235], v[216:219], v[66:81]
	ds_read_b128 v[232:235], v209 offset:31744
	s_waitcnt lgkmcnt(4)
	v_mfma_f32_32x32x16_bf16 v[114:129], v[236:239], v[220:223], v[114:129]
	ds_read_b128 v[236:239], v209 offset:48128
	s_waitcnt lgkmcnt(4)
	v_mfma_f32_32x32x16_bf16 v[66:81], v[240:243], v[220:223], v[66:81]
	s_waitcnt lgkmcnt(3)
	v_mfma_f32_32x32x16_bf16 v[114:129], v[244:247], v[224:227], v[114:129]
	s_waitcnt lgkmcnt(2)
	v_mfma_f32_32x32x16_bf16 v[66:81], v[168:171], v[224:227], v[66:81]
	s_waitcnt lgkmcnt(1)
	v_mfma_f32_32x32x16_bf16 v[114:129], v[232:235], v[228:231], v[114:129]
	s_waitcnt lgkmcnt(0)
	v_mfma_f32_32x32x16_bf16 v[66:81], v[236:239], v[228:231], v[66:81]
	s_nop 7
	s_nop 7
	v_add_u32_e32 v130, v195, v140
	v_add_u32_e32 v131, 0x2000, v130
	v_cvt_pk_bf16_f32 v236, v98, v99
	v_cvt_pk_bf16_f32 v237, v100, v101
	v_cvt_pk_bf16_f32 v238, v102, v103
	v_cvt_pk_bf16_f32 v239, v104, v105
	ds_write2_b64 v131, v[236:237], v[238:239] offset0:64 offset1:66
	v_cvt_pk_bf16_f32 v240, v106, v107
	v_cvt_pk_bf16_f32 v241, v108, v109
	v_cvt_pk_bf16_f32 v242, v110, v111
	v_cvt_pk_bf16_f32 v243, v112, v113
	ds_write2_b64 v131, v[240:241], v[242:243] offset0:68 offset1:70
	v_cvt_pk_bf16_f32 v236, v114, v115
	v_cvt_pk_bf16_f32 v237, v116, v117
	v_cvt_pk_bf16_f32 v238, v118, v119
	v_cvt_pk_bf16_f32 v239, v120, v121
	ds_write2_b64 v131, v[236:237], v[238:239] offset0:72 offset1:74
	v_cvt_pk_bf16_f32 v240, v122, v123
	v_cvt_pk_bf16_f32 v241, v124, v125
	v_cvt_pk_bf16_f32 v242, v126, v127
	v_cvt_pk_bf16_f32 v243, v128, v129
	ds_write2_b64 v131, v[240:241], v[242:243] offset0:76 offset1:78
	s_waitcnt lgkmcnt(0)
	s_and_saveexec_b64 s[8:9], s[0:1]
	v_mov_b32_e32 v98, s34
	ds_write_b32 v163, v98 offset:13324
	s_or_b64 exec, exec, s[8:9]
	ds_read_b32 v98, v163 offset:13320
	s_waitcnt lgkmcnt(0)
	v_cmp_lt_u32_e32 vcc, s7, v98
	s_cbranch_vccnz .LBB0_1515
	s_mov_b32 s4, 1
	s_branch .LBB0_1507

; #define LAS __attribute__((address_space(3)))
; __device__ __forceinline__ f32x16 mma32(bf16x8 a, bf16x8 b, f32x16 c) { return __builtin_amdgcn_mfma_f32_32x32x16_bf16(a, b, c, 0, 0, 0); }
; __device__ __forceinline__ int acc_row(int reg, int hh) { return (reg & 3) + 8 * (reg >> 2) + 4 * hh; }
; __device__ __forceinline__ void gla_scan_task(const P& p, int l, int s, int h, int sl, LAS unsigned char* ldsw, int lane) {
;     ...
;         bf16x8 vb[4];
; #pragma unroll
;         for (int ks = 0; ks < 4; ++ks) vb[ks] = FRAG16(bufA, ks, lane);
; #pragma unroll
;         for (int ti = 0; ti < 2; ++ti) {
;             f32x16 o = zero16();
; #pragma unroll
;             for (int ks = 0; ks < 8; ++ks) { const bf16x8 b = *(const LAS bf16x8*)(ST + r * 136 + 16 * ks + 8 * hh); o = mma32(FRAG16(bufA, 4 + ti * 8 + ks, lane), b, o); }
; #pragma unroll
;             for (int ks = 0; ks < 4; ++ks) o = mma32(FRAG16(bufA, 20 + ti * 4 + ks, lane), vb[ks], o);
; #pragma unroll
;             for (int reg = 0; reg < 16; ++reg) p.OBRAW[(size_t)(r0 + 32 * ti + acc_row(reg, hh)) * 1024 + h * 256 + 32 * sl + r] = o[reg];
.LBB0_1532:
.LBB0_1543:
	s_waitcnt lgkmcnt(0)
	v_add_u32_e32 v172, v194, v148
	v_lshl_add_u32 v132, s34, 6, v134
	s_add_i32 s7, s34, 1
	v_ashrrev_i32_e32 v133, 31, v132
	v_lshlrev_b64 v[136:137], 12, v[132:133]
	v_lshl_add_u64 v[136:137], v[130:131], 0, v[136:137]
	ds_read_b128 v[94:97], v209 offset:16384
	ds_read_b128 v[90:93], v209 offset:17408
	ds_read_b128 v[86:89], v209 offset:18432
	ds_read_b128 v[82:85], v209 offset:19456
	ds_read_b128 v[122:125], v172
	ds_read_b128 v[236:239], v209 offset:20480
	ds_read_b128 v[118:121], v172 offset:32
	ds_read_b128 v[240:243], v209 offset:21504
	ds_read_b128 v[126:129], v172 offset:64
	ds_read_b128 v[244:247], v209 offset:22528
	ds_read_b128 v[114:117], v172 offset:96
	ds_read_b128 v[168:171], v209 offset:23552
	ds_read_b128 v[110:113], v172 offset:128
	ds_read_b128 v[212:215], v209 offset:24576
	s_waitcnt lgkmcnt(8)
	v_mfma_f32_32x32x16_bf16 v[66:81], v[236:239], v[122:125], 0
	ds_read_b128 v[106:109], v172 offset:160
	ds_read_b128 v[216:219], v209 offset:25600
	ds_read_b128 v[102:105], v172 offset:192
	ds_read_b128 v[220:223], v209 offset:26624
	s_waitcnt lgkmcnt(10)
	v_mfma_f32_32x32x16_bf16 v[66:81], v[240:243], v[118:121], v[66:81]
	ds_read_b128 v[98:101], v172 offset:224
	ds_read_b128 v[224:227], v209 offset:27648
	s_waitcnt lgkmcnt(10)
	v_mfma_f32_32x32x16_bf16 v[66:81], v[244:247], v[126:129], v[66:81]
	ds_read_b128 v[228:231], v209 offset:36864
	s_waitcnt lgkmcnt(9)
	v_mfma_f32_32x32x16_bf16 v[66:81], v[168:171], v[114:117], v[66:81]
	ds_read_b128 v[232:235], v209 offset:37888
	s_waitcnt lgkmcnt(8)
	v_mfma_f32_32x32x16_bf16 v[66:81], v[212:215], v[110:113], v[66:81]
	ds_read_b128 v[236:239], v209 offset:38912
	s_waitcnt lgkmcnt(7)
	v_mfma_f32_32x32x16_bf16 v[66:81], v[216:219], v[106:109], v[66:81]
	ds_read_b128 v[240:243], v209 offset:39936
	s_waitcnt lgkmcnt(6)
	v_mfma_f32_32x32x16_bf16 v[66:81], v[220:223], v[102:105], v[66:81]
	s_waitcnt lgkmcnt(4)
	v_mfma_f32_32x32x16_bf16 v[66:81], v[224:227], v[98:101], v[66:81]
	s_waitcnt lgkmcnt(3)
	v_mfma_f32_32x32x16_bf16 v[66:81], v[228:231], v[94:97], v[66:81]
	s_waitcnt lgkmcnt(2)
	v_mfma_f32_32x32x16_bf16 v[66:81], v[232:235], v[90:93], v[66:81]
	s_waitcnt lgkmcnt(1)
	v_mfma_f32_32x32x16_bf16 v[66:81], v[236:239], v[86:89], v[66:81]
	s_waitcnt lgkmcnt(0)
	v_mfma_f32_32x32x16_bf16 v[66:81], v[240:243], v[82:85], v[66:81]
	s_and_saveexec_b64 s[100:101], s[0:1]
	v_mov_b32_e32 v255, s7
	ds_write_b32 v163, v255 offset:13336
	s_or_b64 exec, exec, s[100:101]
	s_nop 11
	global_store_dword v[136:137], v66, off
	v_or_b32_e32 v136, 1, v132
	v_ashrrev_i32_e32 v137, 31, v136
	v_lshlrev_b64 v[136:137], 12, v[136:137]
	v_lshl_add_u64 v[136:137], v[130:131], 0, v[136:137]
	v_or_b32_e32 v66, 2, v132
	global_store_dword v[136:137], v67, off
	v_ashrrev_i32_e32 v67, 31, v66
	v_lshlrev_b64 v[66:67], 12, v[66:67]
	v_lshl_add_u64 v[66:67], v[130:131], 0, v[66:67]
	global_store_dword v[66:67], v68, off
	v_or_b32_e32 v66, 3, v132
	v_ashrrev_i32_e32 v67, 31, v66
	v_lshlrev_b64 v[66:67], 12, v[66:67]
	v_lshl_add_u64 v[66:67], v[130:131], 0, v[66:67]
	global_store_dword v[66:67], v69, off
	v_or_b32_e32 v66, 8, v132
	v_ashrrev_i32_e32 v67, 31, v66
	v_lshlrev_b64 v[66:67], 12, v[66:67]
	v_lshl_add_u64 v[66:67], v[130:131], 0, v[66:67]
	global_store_dword v[66:67], v70, off
	v_or_b32_e32 v66, 9, v132
	v_ashrrev_i32_e32 v67, 31, v66
	v_lshlrev_b64 v[66:67], 12, v[66:67]
	v_lshl_add_u64 v[66:67], v[130:131], 0, v[66:67]
	global_store_dword v[66:67], v71, off
	v_or_b32_e32 v66, 10, v132
	v_ashrrev_i32_e32 v67, 31, v66
	v_lshlrev_b64 v[66:67], 12, v[66:67]
	v_lshl_add_u64 v[66:67], v[130:131], 0, v[66:67]
	global_store_dword v[66:67], v72, off
	v_or_b32_e32 v66, 11, v132
	v_ashrrev_i32_e32 v67, 31, v66
	v_lshlrev_b64 v[66:67], 12, v[66:67]
	v_lshl_add_u64 v[66:67], v[130:131], 0, v[66:67]
	global_store_dword v[66:67], v73, off
	v_or_b32_e32 v66, 16, v132
	v_ashrrev_i32_e32 v67, 31, v66
	v_lshlrev_b64 v[66:67], 12, v[66:67]
	v_lshl_add_u64 v[66:67], v[130:131], 0, v[66:67]
	global_store_dword v[66:67], v74, off
	v_or_b32_e32 v66, 17, v132
	v_ashrrev_i32_e32 v67, 31, v66
	v_lshlrev_b64 v[66:67], 12, v[66:67]
	v_lshl_add_u64 v[66:67], v[130:131], 0, v[66:67]
	global_store_dword v[66:67], v75, off
	v_or_b32_e32 v66, 18, v132
	v_ashrrev_i32_e32 v67, 31, v66
	v_lshlrev_b64 v[66:67], 12, v[66:67]
	v_lshl_add_u64 v[66:67], v[130:131], 0, v[66:67]
	global_store_dword v[66:67], v76, off
	v_or_b32_e32 v66, 19, v132
	v_ashrrev_i32_e32 v67, 31, v66
	v_lshlrev_b64 v[66:67], 12, v[66:67]
	v_lshl_add_u64 v[66:67], v[130:131], 0, v[66:67]
	global_store_dword v[66:67], v77, off
	v_or_b32_e32 v66, 24, v132
	v_ashrrev_i32_e32 v67, 31, v66
	v_lshlrev_b64 v[66:67], 12, v[66:67]
	v_lshl_add_u64 v[66:67], v[130:131], 0, v[66:67]
	global_store_dword v[66:67], v78, off
	v_or_b32_e32 v66, 25, v132
	v_ashrrev_i32_e32 v67, 31, v66
	v_lshlrev_b64 v[66:67], 12, v[66:67]
	v_lshl_add_u64 v[66:67], v[130:131], 0, v[66:67]
	global_store_dword v[66:67], v79, off
	v_or_b32_e32 v66, 26, v132
	v_ashrrev_i32_e32 v67, 31, v66
	v_lshlrev_b64 v[66:67], 12, v[66:67]
	v_lshl_add_u64 v[66:67], v[130:131], 0, v[66:67]
	global_store_dword v[66:67], v80, off
	v_or_b32_e32 v66, 27, v132
	v_ashrrev_i32_e32 v67, 31, v66
	v_lshlrev_b64 v[66:67], 12, v[66:67]
	v_lshl_add_u64 v[66:67], v[130:131], 0, v[66:67]
	global_store_dword v[66:67], v81, off
	s_waitcnt lgkmcnt(0)
	ds_read_b32 v255, v163 offset:13316
	s_waitcnt lgkmcnt(0)
	v_cmp_lt_u32_e32 vcc, s34, v255
	s_cbranch_vccnz .Lgp1_done
	s_mov_b32 s4, 1
	s_branch .Lgp1_1535

; #define LAS __attribute__((address_space(3)))
; template <bool SLEEP = false> __device__ __forceinline__ bool lds_wait_ge(volatile LAS unsigned* w, unsigned need, volatile LAS unsigned* abortw) {
;     unsigned sp = 0; bool ok = true;
;     while (*w < need) { if (SLEEP) __builtin_amdgcn_s_sleep(1); if ((++sp & 1023u) == 0u) { if (*abortw != 0u) { ok = false; break; } if (sp > (1u << 22)) { *abortw = 1u; ok = false; break; } } }
;     __builtin_amdgcn_fence(__ATOMIC_ACQUIRE, "workgroup");
;     asm volatile("" ::: "memory");
;     return ok;
; }
.Lgp1_1537:
	ds_read_b32 v255, v163 offset:13316
	s_add_i32 s4, s4, 1
	s_mov_b64 s[10:11], -1
	s_waitcnt lgkmcnt(0)
	v_cmp_lt_u32_e64 s[8:9], s34, v255
	s_branch .Lgp1_1534
.Lgp1_1538:
	ds_read_b32 v255, v163 offset:13332
	s_waitcnt lgkmcnt(0)
	v_cmp_eq_u32_e32 vcc, 0, v255
	s_cbranch_vccnz .Lgp1_1540
	s_mov_b64 s[10:11], -1
	s_branch .Lgp1_1534

; #define LAS __attribute__((address_space(3)))
; __device__ __forceinline__ f32x16 mma32(bf16x8 a, bf16x8 b, f32x16 c) { return __builtin_amdgcn_mfma_f32_32x32x16_bf16(a, b, c, 0, 0, 0); }
; __device__ __forceinline__ int acc_row(int reg, int hh) { return (reg & 3) + 8 * (reg >> 2) + 4 * hh; }
; #define LDS_WAIT() asm volatile("s_waitcnt lgkmcnt(0)" ::: "memory")
; __device__ __forceinline__ void gla_scan_task(const P& p, int l, int s, int h, int sl, LAS unsigned char* ldsw, int lane) {
;     ...
;         for (int ti = 0; ti < 2; ++ti) {
;             f32x16 o = zero16();
; #pragma unroll
;             for (int ks = 0; ks < 8; ++ks) { const bf16x8 b = *(const LAS bf16x8*)(ST + r * 136 + 16 * ks + 8 * hh); o = mma32(FRAG16(bufA, 4 + ti * 8 + ks, lane), b, o); }
; #pragma unroll
;             for (int ks = 0; ks < 4; ++ks) o = mma32(FRAG16(bufA, 20 + ti * 4 + ks, lane), vb[ks], o);
; #pragma unroll
;             for (int reg = 0; reg < 16; ++reg) p.OBRAW[(size_t)(r0 + 32 * ti + acc_row(reg, hh)) * 1024 + h * 256 + 32 * sl + r] = o[reg];
;         }
;         LDS_WAIT();
;         if (SCAN_LOADERS) { if (lane == 0) FL[3] = (unsigned)n + 1u; lds_wait_ge(FL + 2, (unsigned)n + 1u, FL + 5); }
.Lgp1_done:
	s_waitcnt lgkmcnt(0)
	ds_read_b128 v[236:239], v209 offset:28672
	ds_read_b128 v[240:243], v209 offset:29696
	ds_read_b128 v[244:247], v209 offset:30720
	ds_read_b128 v[168:171], v209 offset:31744
	ds_read_b128 v[212:215], v209 offset:32768
	ds_read_b128 v[216:219], v209 offset:33792
	s_waitcnt lgkmcnt(5)
	v_mfma_f32_32x32x16_bf16 v[66:81], v[236:239], v[122:125], 0
	ds_read_b128 v[220:223], v209 offset:34816
	s_waitcnt lgkmcnt(5)
	v_mfma_f32_32x32x16_bf16 v[66:81], v[240:243], v[118:121], v[66:81]
	ds_read_b128 v[224:227], v209 offset:35840
	s_waitcnt lgkmcnt(5)
	v_mfma_f32_32x32x16_bf16 v[66:81], v[244:247], v[126:129], v[66:81]
	ds_read_b128 v[228:231], v209 offset:40960
	s_waitcnt lgkmcnt(5)
	v_mfma_f32_32x32x16_bf16 v[66:81], v[168:171], v[114:117], v[66:81]
	ds_read_b128 v[232:235], v209 offset:41984
	s_waitcnt lgkmcnt(5)
	v_mfma_f32_32x32x16_bf16 v[66:81], v[212:215], v[110:113], v[66:81]
	ds_read_b128 v[236:239], v209 offset:43008
	s_waitcnt lgkmcnt(5)
	v_mfma_f32_32x32x16_bf16 v[66:81], v[216:219], v[106:109], v[66:81]
	ds_read_b128 v[240:243], v209 offset:44032
	s_waitcnt lgkmcnt(5)
	v_mfma_f32_32x32x16_bf16 v[66:81], v[220:223], v[102:105], v[66:81]
	s_waitcnt lgkmcnt(4)
	v_mfma_f32_32x32x16_bf16 v[66:81], v[224:227], v[98:101], v[66:81]
	s_waitcnt lgkmcnt(3)
	v_mfma_f32_32x32x16_bf16 v[66:81], v[228:231], v[94:97], v[66:81]
	s_waitcnt lgkmcnt(2)
	v_mfma_f32_32x32x16_bf16 v[66:81], v[232:235], v[90:93], v[66:81]
	s_waitcnt lgkmcnt(1)
	v_mfma_f32_32x32x16_bf16 v[66:81], v[236:239], v[86:89], v[66:81]
	s_waitcnt lgkmcnt(0)
	v_mfma_f32_32x32x16_bf16 v[66:81], v[240:243], v[82:85], v[66:81]
	v_or_b32_e32 v98, 32, v132
	v_ashrrev_i32_e32 v99, 31, v98
	v_lshlrev_b64 v[98:99], 12, v[98:99]
	v_lshl_add_u64 v[98:99], v[130:131], 0, v[98:99]
	s_nop 7
	global_store_dword v[98:99], v66, off
	v_or_b32_e32 v98, 33, v132
	v_ashrrev_i32_e32 v99, 31, v98
	v_lshlrev_b64 v[98:99], 12, v[98:99]
	v_lshl_add_u64 v[98:99], v[130:131], 0, v[98:99]
	v_or_b32_e32 v66, 34, v132
	global_store_dword v[98:99], v67, off
	v_ashrrev_i32_e32 v67, 31, v66
	v_lshlrev_b64 v[66:67], 12, v[66:67]
	v_lshl_add_u64 v[66:67], v[130:131], 0, v[66:67]
	global_store_dword v[66:67], v68, off
	v_or_b32_e32 v66, 35, v132
	v_ashrrev_i32_e32 v67, 31, v66
	v_lshlrev_b64 v[66:67], 12, v[66:67]
	v_lshl_add_u64 v[66:67], v[130:131], 0, v[66:67]
	global_store_dword v[66:67], v69, off
	v_or_b32_e32 v66, 40, v132
	v_ashrrev_i32_e32 v67, 31, v66
	v_lshlrev_b64 v[66:67], 12, v[66:67]
	v_lshl_add_u64 v[66:67], v[130:131], 0, v[66:67]
	global_store_dword v[66:67], v70, off
	v_or_b32_e32 v66, 41, v132
	v_ashrrev_i32_e32 v67, 31, v66
	v_lshlrev_b64 v[66:67], 12, v[66:67]
	v_lshl_add_u64 v[66:67], v[130:131], 0, v[66:67]
	global_store_dword v[66:67], v71, off
	v_or_b32_e32 v66, 42, v132
	v_ashrrev_i32_e32 v67, 31, v66
	v_lshlrev_b64 v[66:67], 12, v[66:67]
	v_lshl_add_u64 v[66:67], v[130:131], 0, v[66:67]
	global_store_dword v[66:67], v72, off
	v_or_b32_e32 v66, 43, v132
	v_ashrrev_i32_e32 v67, 31, v66
	v_lshlrev_b64 v[66:67], 12, v[66:67]
	v_lshl_add_u64 v[66:67], v[130:131], 0, v[66:67]
	global_store_dword v[66:67], v73, off
	v_or_b32_e32 v66, 48, v132
	v_ashrrev_i32_e32 v67, 31, v66
	v_lshlrev_b64 v[66:67], 12, v[66:67]
	v_lshl_add_u64 v[66:67], v[130:131], 0, v[66:67]
	global_store_dword v[66:67], v74, off
	v_or_b32_e32 v66, 49, v132
	v_ashrrev_i32_e32 v67, 31, v66
	v_lshlrev_b64 v[66:67], 12, v[66:67]
	v_lshl_add_u64 v[66:67], v[130:131], 0, v[66:67]
	global_store_dword v[66:67], v75, off
	v_or_b32_e32 v66, 50, v132
	v_ashrrev_i32_e32 v67, 31, v66
	v_lshlrev_b64 v[66:67], 12, v[66:67]
	v_lshl_add_u64 v[66:67], v[130:131], 0, v[66:67]
	global_store_dword v[66:67], v76, off
	v_or_b32_e32 v66, 51, v132
	v_ashrrev_i32_e32 v67, 31, v66
	v_lshlrev_b64 v[66:67], 12, v[66:67]
	v_lshl_add_u64 v[66:67], v[130:131], 0, v[66:67]
	global_store_dword v[66:67], v77, off
	v_or_b32_e32 v66, 56, v132
	v_ashrrev_i32_e32 v67, 31, v66
	v_lshlrev_b64 v[66:67], 12, v[66:67]
	v_lshl_add_u64 v[66:67], v[130:131], 0, v[66:67]
	global_store_dword v[66:67], v78, off
	v_or_b32_e32 v66, 57, v132
	v_ashrrev_i32_e32 v67, 31, v66
	v_lshlrev_b64 v[66:67], 12, v[66:67]
	v_lshl_add_u64 v[66:67], v[130:131], 0, v[66:67]
	global_store_dword v[66:67], v79, off
	v_or_b32_e32 v66, 58, v132
	v_ashrrev_i32_e32 v67, 31, v66
	v_lshlrev_b64 v[66:67], 12, v[66:67]
	v_lshl_add_u64 v[66:67], v[130:131], 0, v[66:67]
	global_store_dword v[66:67], v80, off
	v_or_b32_e32 v66, 59, v132
	v_ashrrev_i32_e32 v67, 31, v66
	v_lshlrev_b64 v[66:67], 12, v[66:67]
	v_lshl_add_u64 v[66:67], v[130:131], 0, v[66:67]
	global_store_dword v[66:67], v81, off
	s_waitcnt lgkmcnt(0)
	s_and_saveexec_b64 s[8:9], s[0:1]
	v_mov_b32_e32 v66, s7
	ds_write_b32 v163, v66 offset:13324
	s_or_b64 exec, exec, s[8:9]
	ds_read_b32 v66, v163 offset:13320
	s_waitcnt lgkmcnt(0)
	v_cmp_lt_u32_e32 vcc, s34, v66
	s_cbranch_vccnz .LBB0_1556
	s_mov_b32 s4, 1
	s_branch .LBB0_1548

; __global__ void __launch_bounds__(512, 2) mega(Args a) {
	.amdhsa_kernel _Z4mega4Args
		.amdhsa_group_segment_fixed_size 0
		.amdhsa_private_segment_fixed_size 0
		.amdhsa_kernarg_size 872
		.amdhsa_user_sgpr_count 2
		.amdhsa_user_sgpr_dispatch_ptr 0
		.amdhsa_user_sgpr_queue_ptr 0
		.amdhsa_user_sgpr_kernarg_segment_ptr 1
		.amdhsa_user_sgpr_dispatch_id 0
		.amdhsa_user_sgpr_kernarg_preload_length 0
		.amdhsa_user_sgpr_kernarg_preload_offset 0
		.amdhsa_user_sgpr_private_segment_size 0
		.amdhsa_uses_dynamic_stack 0
		.amdhsa_enable_private_segment 0
		.amdhsa_system_sgpr_workgroup_id_x 1
		.amdhsa_system_sgpr_workgroup_id_y 0
		.amdhsa_system_sgpr_workgroup_id_z 0
		.amdhsa_system_sgpr_workgroup_info 0
		.amdhsa_system_vgpr_workitem_id 0
		.amdhsa_next_free_vgpr 256
		.amdhsa_next_free_sgpr 102
		.amdhsa_accum_offset 256
		.amdhsa_reserve_vcc 1
		.amdhsa_float_round_mode_32 0
		.amdhsa_float_round_mode_16_64 0
		.amdhsa_float_denorm_mode_32 3
		.amdhsa_float_denorm_mode_16_64 3
		.amdhsa_dx10_clamp 1
		.amdhsa_ieee_mode 1
		.amdhsa_fp16_overflow 0
		.amdhsa_tg_split 0
		.amdhsa_exception_fp_ieee_invalid_op 0
		.amdhsa_exception_fp_denorm_src 0
		.amdhsa_exception_fp_ieee_div_zero 0
		.amdhsa_exception_fp_ieee_overflow 0
		.amdhsa_exception_fp_ieee_underflow 0
		.amdhsa_exception_fp_ieee_inexact 0
		.amdhsa_exception_int_div_zero 0
	.end_amdhsa_kernel

; __global__ void __launch_bounds__(512, 2) mega(Args a) {
amdhsa.kernels:
  - .agpr_count:     0
    .args:
      - .offset:         0
        .size:           616
        .value_kind:     by_value
      - .offset:         616
        .size:           4
        .value_kind:     hidden_block_count_x
      - .offset:         620
        .size:           4
        .value_kind:     hidden_block_count_y
      - .offset:         624
        .size:           4
        .value_kind:     hidden_block_count_z
      - .offset:         628
        .size:           2
        .value_kind:     hidden_group_size_x
      - .offset:         630
        .size:           2
        .value_kind:     hidden_group_size_y
      - .offset:         632
        .size:           2
        .value_kind:     hidden_group_size_z
      - .offset:         634
        .size:           2
        .value_kind:     hidden_remainder_x
      - .offset:         636
        .size:           2
        .value_kind:     hidden_remainder_y
      - .offset:         638
        .size:           2
        .value_kind:     hidden_remainder_z
      - .offset:         656
        .size:           8
        .value_kind:     hidden_global_offset_x
      - .offset:         664
        .size:           8
        .value_kind:     hidden_global_offset_y
      - .offset:         672
        .size:           8
        .value_kind:     hidden_global_offset_z
      - .offset:         680
        .size:           2
        .value_kind:     hidden_grid_dims
      - .offset:         736
        .size:           4
        .value_kind:     hidden_dynamic_lds_size
    .group_segment_fixed_size: 0
    .kernarg_segment_align: 8
    .kernarg_segment_size: 872
    .language:       OpenCL C
    .language_version:
      - 2
      - 0
    .max_flat_workgroup_size: 512
    .name:           _Z4mega4Args
    .private_segment_fixed_size: 0
    .sgpr_count:     108
    .sgpr_spill_count: 434
    .symbol:         _Z4mega4Args.kd
    .uniform_work_group_size: 1
    .uses_dynamic_stack: false
    .vgpr_count:     256
    .vgpr_spill_count: 0
    .wavefront_size: 64
